# attention tile loop: branch-free fast check that tile tt+1 is valid (bypasses the next-tile search loop and its taken branches in the common case; original search kept as fallback)
# speedup vs baseline: 1.0092x; 1.0092x over previous
.LBB0_135:
	s_lshl_b32 s53, s74, 5
	s_add_i32 s71, s74, 1
	s_cmp_gt_i32 s74, 21
	s_cbranch_scc1 .Lnt_slow_b
	s_lshl_b32 s4, s71, 7
	s_sub_i32 s5, s67, s4
	s_add_i32 s6, s68, s4
	s_cmp_gt_u32 s71, 10
	s_cselect_b32 s5, s5, s6
	s_add_i32 s5, s5, 0x7c
	s_add_i32 s6, s70, s53
	s_add_i32 s6, s6, 31
	s_cmp_lt_u32 s71, 8
	s_cselect_b32 s5, s6, s5
	s_cmp_gt_i32 s5, -1
	s_cbranch_scc1 .LBB0_145
.Lnt_slow_b:
	s_max_i32 s38, s74, 22
	s_add_i32 s38, s38, 1
	s_add_i32 s39, s70, s53
	s_mov_b32 s52, s74
	s_branch .LBB0_139

.LBB0_162:
	v_sub_f32_e32 v14, v14, v162
	v_sub_f32_e32 v15, v15, v162
	v_exp_f32_e32 v14, v14
	v_sub_f32_e32 v164, v164, v162
	v_sub_f32_e32 v165, v165, v162
	v_exp_f32_e32 v15, v15
	v_sub_f32_e32 v163, v163, v162
	v_add_f32_e32 v167, 0, v14
	v_exp_f32_e32 v169, v164
	v_add_f32_e32 v164, v167, v15
	v_exp_f32_e32 v167, v165
	v_sub_f32_e32 v165, v166, v162
	s_waitcnt lgkmcnt(0)
	s_nop 0
	v_exp_f32_e32 v166, v165
	v_sub_f32_e32 v165, v168, v162
	v_exp_f32_e32 v163, v163
	v_exp_f32_e32 v168, v165
	v_sub_f32_e32 v165, v170, v162
	s_nop 0
	v_exp_f32_e32 v170, v165
	v_sub_f32_e32 v165, v171, v162
	v_add_f32_e32 v164, v164, v163
	v_exp_f32_e32 v171, v165
	v_sub_f32_e32 v165, v172, v162
	v_add_f32_e32 v164, v164, v169
	v_exp_f32_e32 v172, v165
	v_sub_f32_e32 v165, v173, v162
	v_add_f32_e32 v164, v164, v167
	v_add_f32_e32 v164, v164, v166
	v_exp_f32_e32 v173, v165
	v_sub_f32_e32 v165, v174, v162
	v_add_f32_e32 v164, v164, v168
	v_cvt_pk_bf16_f32 v166, v167, v166
	v_add_f32_e32 v164, v164, v170
	v_exp_f32_e32 v174, v165
	v_sub_f32_e32 v165, v175, v162
	v_add_f32_e32 v164, v164, v171
	v_add_f32_e32 v164, v164, v172
	v_exp_f32_e32 v175, v165
	v_sub_f32_e32 v165, v176, v162
	v_add_f32_e32 v164, v164, v173
	v_cvt_pk_bf16_f32 v167, v168, v170
	v_exp_f32_e32 v176, v165
	v_add_f32_e32 v164, v164, v174
	v_sub_f32_e32 v165, v177, v162
	v_add_f32_e32 v164, v164, v175
	v_cvt_pk_bf16_f32 v168, v171, v172
	v_exp_f32_e32 v177, v165
	v_sub_f32_e32 v165, v178, v162
	v_add_f32_e32 v164, v164, v176
	v_cvt_pk_bf16_f32 v170, v175, v176
	v_exp_f32_e32 v178, v165
	v_add_f32_e32 v164, v164, v177
	v_cvt_pk_bf16_f32 v165, v163, v169
	v_add_f32_e32 v164, v164, v178
	v_add_f32_e32 v143, v143, v164
	v_cvt_pk_bf16_f32 v164, v14, v15
	v_cvt_pk_bf16_f32 v169, v173, v174
	v_cvt_pk_bf16_f32 v171, v177, v178
	s_setprio 1
	v_mfma_f32_32x32x16_bf16 v[16:31], v[60:63], v[164:167], v[16:31]
	v_mfma_f32_32x32x16_bf16 v[32:47], v[52:55], v[164:167], v[32:47]
	v_mfma_f32_32x32x16_bf16 v[16:31], v[56:59], v[168:171], v[16:31]
	v_mfma_f32_32x32x16_bf16 v[32:47], v[48:51], v[168:171], v[32:47]
	s_setprio 0
	s_cmp_gt_i32 s71, 22
	s_cbranch_scc1 .LBB0_134
	s_lshl_b32 s72, s71, 5
	s_add_i32 s74, s71, 1
	s_cmp_gt_i32 s71, 21
	s_cbranch_scc1 .Lnt_slow_a
	s_lshl_b32 s4, s74, 7
	s_sub_i32 s5, s67, s4
	s_add_i32 s6, s68, s4
	s_cmp_gt_u32 s74, 10
	s_cselect_b32 s5, s5, s6
	s_add_i32 s5, s5, 0x7c
	s_add_i32 s6, s70, s72
	s_add_i32 s6, s6, 31
	s_cmp_lt_u32 s74, 8
	s_cselect_b32 s5, s6, s5
	s_cmp_gt_i32 s5, -1
	s_cbranch_scc1 .LBB0_173
.Lnt_slow_a:
	s_add_i32 s38, s70, s72
	s_mov_b32 s36, s71
	s_branch .LBB0_166
